# MLP-in epilogue: dropped the 128 canonicalising v_max before relu (max(0,x) alone is identical), on top of local barriers
# speedup vs baseline: 1.0414x; 1.0032x over previous
; __device__ __forceinline__ unsigned cvt_pk_bf16(float lo, float hi) { f32x2 v = {lo, hi}; bf16x2_t b = __builtin_convertvector(v, bf16x2_t); return __builtin_bit_cast(unsigned, b); }
;     __device__ __forceinline__ void operator()(const f32x4 (&acc)[2][2][4][2], const Unit& u, int wr, int wc, int fr, int fq) const {
;     ...
;             for (int m = 0; m < 4; ++m) {
;                 const int row = row0 + ai * HALF + m * 16;
;                 float sc = 1.f; u32x4 bw0, bw1;
;                 if (has_scale) sc = xl[2560 + ai * HALF + wr * 64 + m * 16 + fr];
;                 if (MODE == 3) { bw0 = bnn[m][0]; bw1 = bnn[m][1]; }
;                 if (MODE == 0 || MODE == 1) {
; #pragma unroll
;                     for (int bj = 0; bj < 2; ++bj) {
;                         const int hf = 2 * u.pn + bj;
;                         bf16_t* dst;
;                         if (split2) dst = ((hf & 1) ? O2 : O) + (size_t)row * ldc + (hf >> 1) * 128 + wc * 32 + 8 * fq;
;                         else dst = O + (size_t)row * ldc + hf * 128 + wc * 32 + 8 * fq;
;                         f32x4 v0 = acc[ai][bj][m][0] * sc, v1 = acc[ai][bj][m][1] * sc;
;                         if (MODE == 1) {
; #pragma unroll
;                             for (int e = 0; e < 4; ++e) { float a = fmaxf(v0[e], 0.f), b = fmaxf(v1[e], 0.f); v0[e] = a * a; v1[e] = b * b; }
;                         }
;                         u32x4 w; w.x = cvt_pk_bf16(v0[0], v0[1]); w.y = cvt_pk_bf16(v0[2], v0[3]); w.z = cvt_pk_bf16(v1[0], v1[1]); w.w = cvt_pk_bf16(v1[2], v1[3]);
;                         if (MODE == 1) asm volatile("global_store_dwordx4 %0, %1, off sc1\n\ts_nop 1" :: "v"(dst), "v"(w) : "memory");
;                         else *(u32x4*)dst = w;
;                     }
.LBB0_1070:
	v_lshl_add_u32 v142, s46, 8, v144
	s_lshl_b32 s6, s44, 8
	v_ashrrev_i32_e32 v143, 31, v142
	v_max_f32_e32 v120, 0, v120
	v_max_f32_e32 v121, 0, v121
	v_lshlrev_b64 v[140:141], 13, v[142:143]
	s_ashr_i32 s7, s6, 31
	v_pk_mul_f32 v[148:149], v[120:121], v[120:121]
	v_lshl_add_u64 v[140:141], s[88:89], 0, v[140:141]
	s_lshl_b64 s[6:7], s[6:7], 1
	v_max_f32_e32 v122, 0, v122
	v_max_f32_e32 v123, 0, v123
	v_lshl_add_u64 v[140:141], v[140:141], 0, s[6:7]
	v_max_f32_e32 v124, 0, v124
	v_max_f32_e32 v125, 0, v125
	v_max_f32_e32 v120, 0, v126
	v_max_f32_e32 v121, 0, v127
	v_pk_mul_f32 v[150:151], v[122:123], v[122:123]
	v_lshl_add_u64 v[140:141], v[140:141], 0, s[50:51]
	v_pk_mul_f32 v[124:125], v[124:125], v[124:125]
	v_pk_mul_f32 v[126:127], v[120:121], v[120:121]
	v_cvt_pk_bf16_f32 v122, v148, v149
	v_cvt_pk_bf16_f32 v123, v150, v151
	v_max_f32_e32 v112, 0, v112
	v_max_f32_e32 v113, 0, v113
	v_lshl_add_u64 v[140:141], v[140:141], 0, v[180:181]
	v_cvt_pk_bf16_f32 v120, v124, v125
	v_cvt_pk_bf16_f32 v121, v126, v127
	global_store_dwordx4 v[140:141], v[120:123], off sc1
	s_nop 1
	v_pk_mul_f32 v[122:123], v[112:113], v[112:113]
	v_max_f32_e32 v116, 0, v116
	v_max_f32_e32 v117, 0, v117
	v_max_f32_e32 v114, 0, v114
	v_pk_mul_f32 v[116:117], v[116:117], v[116:117]
	v_max_f32_e32 v112, 0, v118
	v_max_f32_e32 v113, 0, v119
	v_max_f32_e32 v115, 0, v115
	s_mov_b64 s[26:27], 0x100
	v_pk_mul_f32 v[118:119], v[112:113], v[112:113]
	v_pk_mul_f32 v[124:125], v[114:115], v[114:115]
	v_cvt_pk_bf16_f32 v112, v116, v117
	v_lshl_add_u64 v[120:121], v[140:141], 0, s[26:27]
	v_cvt_pk_bf16_f32 v113, v118, v119
	v_cvt_pk_bf16_f32 v114, v122, v123
	v_cvt_pk_bf16_f32 v115, v124, v125
	global_store_dwordx4 v[120:121], v[112:115], off sc1
	s_nop 1
	v_or_b32_e32 v112, 16, v142
	v_ashrrev_i32_e32 v113, 31, v112
	v_max_f32_e32 v104, 0, v104
	v_max_f32_e32 v105, 0, v105
	v_lshlrev_b64 v[112:113], 13, v[112:113]
	v_pk_mul_f32 v[114:115], v[104:105], v[104:105]
	v_lshl_add_u64 v[112:113], s[88:89], 0, v[112:113]
	v_max_f32_e32 v106, 0, v106
	v_max_f32_e32 v107, 0, v107
	v_lshl_add_u64 v[112:113], v[112:113], 0, s[6:7]
	v_max_f32_e32 v108, 0, v108
	v_max_f32_e32 v109, 0, v109
	v_max_f32_e32 v104, 0, v110
	v_max_f32_e32 v105, 0, v111
	v_pk_mul_f32 v[116:117], v[106:107], v[106:107]
	v_lshl_add_u64 v[112:113], v[112:113], 0, s[50:51]
	v_pk_mul_f32 v[108:109], v[108:109], v[108:109]
	v_pk_mul_f32 v[110:111], v[104:105], v[104:105]
	v_cvt_pk_bf16_f32 v106, v114, v115
	v_cvt_pk_bf16_f32 v107, v116, v117
	v_max_f32_e32 v96, 0, v96
	v_max_f32_e32 v97, 0, v97
	v_lshl_add_u64 v[112:113], v[112:113], 0, v[180:181]
	v_cvt_pk_bf16_f32 v104, v108, v109
	v_cvt_pk_bf16_f32 v105, v110, v111
	global_store_dwordx4 v[112:113], v[104:107], off sc1
	s_nop 1
	v_pk_mul_f32 v[106:107], v[96:97], v[96:97]
	v_max_f32_e32 v100, 0, v100
	v_max_f32_e32 v101, 0, v101
	v_max_f32_e32 v98, 0, v98
	v_pk_mul_f32 v[100:101], v[100:101], v[100:101]
	v_max_f32_e32 v96, 0, v102
	v_max_f32_e32 v97, 0, v103
	v_max_f32_e32 v99, 0, v99
	v_pk_mul_f32 v[102:103], v[96:97], v[96:97]
	v_pk_mul_f32 v[108:109], v[98:99], v[98:99]
	v_cvt_pk_bf16_f32 v96, v100, v101
	v_lshl_add_u64 v[104:105], v[112:113], 0, s[26:27]
	v_cvt_pk_bf16_f32 v97, v102, v103
	v_cvt_pk_bf16_f32 v98, v106, v107
	v_cvt_pk_bf16_f32 v99, v108, v109
	global_store_dwordx4 v[104:105], v[96:99], off sc1
	s_nop 1
	v_or_b32_e32 v96, 32, v142
	v_ashrrev_i32_e32 v97, 31, v96
	v_max_f32_e32 v88, 0, v88
	v_max_f32_e32 v89, 0, v89
	v_lshlrev_b64 v[96:97], 13, v[96:97]
	v_pk_mul_f32 v[98:99], v[88:89], v[88:89]
	v_lshl_add_u64 v[96:97], s[88:89], 0, v[96:97]
	v_max_f32_e32 v90, 0, v90
	v_max_f32_e32 v91, 0, v91
	v_lshl_add_u64 v[96:97], v[96:97], 0, s[6:7]
	v_max_f32_e32 v92, 0, v92
	v_max_f32_e32 v93, 0, v93
	v_max_f32_e32 v88, 0, v94
	v_max_f32_e32 v89, 0, v95
	v_pk_mul_f32 v[100:101], v[90:91], v[90:91]
	v_lshl_add_u64 v[96:97], v[96:97], 0, s[50:51]
	v_pk_mul_f32 v[92:93], v[92:93], v[92:93]
	v_pk_mul_f32 v[94:95], v[88:89], v[88:89]
	v_cvt_pk_bf16_f32 v90, v98, v99
	v_cvt_pk_bf16_f32 v91, v100, v101
	v_max_f32_e32 v80, 0, v80
	v_max_f32_e32 v81, 0, v81
	v_lshl_add_u64 v[96:97], v[96:97], 0, v[180:181]
	v_cvt_pk_bf16_f32 v88, v92, v93
	v_cvt_pk_bf16_f32 v89, v94, v95
	global_store_dwordx4 v[96:97], v[88:91], off sc1
	s_nop 1
	v_pk_mul_f32 v[90:91], v[80:81], v[80:81]
	v_max_f32_e32 v84, 0, v84
	v_max_f32_e32 v85, 0, v85
	v_max_f32_e32 v82, 0, v82
	v_pk_mul_f32 v[84:85], v[84:85], v[84:85]
	v_max_f32_e32 v80, 0, v86
	v_max_f32_e32 v81, 0, v87
	v_max_f32_e32 v83, 0, v83
	v_pk_mul_f32 v[86:87], v[80:81], v[80:81]
	v_pk_mul_f32 v[92:93], v[82:83], v[82:83]
	v_cvt_pk_bf16_f32 v80, v84, v85
	v_lshl_add_u64 v[88:89], v[96:97], 0, s[26:27]
	v_cvt_pk_bf16_f32 v81, v86, v87
	v_cvt_pk_bf16_f32 v82, v90, v91
	v_cvt_pk_bf16_f32 v83, v92, v93
	global_store_dwordx4 v[88:89], v[80:83], off sc1
	s_nop 1
	v_or_b32_e32 v80, 48, v142
	v_ashrrev_i32_e32 v81, 31, v80
	v_max_f32_e32 v72, 0, v72
	v_max_f32_e32 v73, 0, v73
	v_lshlrev_b64 v[80:81], 13, v[80:81]
	v_pk_mul_f32 v[82:83], v[72:73], v[72:73]
	v_lshl_add_u64 v[80:81], s[88:89], 0, v[80:81]
	v_max_f32_e32 v74, 0, v74
	v_max_f32_e32 v75, 0, v75
	v_lshl_add_u64 v[80:81], v[80:81], 0, s[6:7]
	v_max_f32_e32 v76, 0, v76
	v_max_f32_e32 v77, 0, v77
	v_max_f32_e32 v72, 0, v78
	v_max_f32_e32 v73, 0, v79
	v_pk_mul_f32 v[84:85], v[74:75], v[74:75]
	v_lshl_add_u64 v[80:81], v[80:81], 0, s[50:51]
	v_pk_mul_f32 v[76:77], v[76:77], v[76:77]
	v_pk_mul_f32 v[78:79], v[72:73], v[72:73]
	v_cvt_pk_bf16_f32 v74, v82, v83
	v_cvt_pk_bf16_f32 v75, v84, v85
	v_max_f32_e32 v64, 0, v64
	v_max_f32_e32 v65, 0, v65
	v_lshl_add_u64 v[80:81], v[80:81], 0, v[180:181]
;     __device__ __forceinline__ void operator()(const f32x4 (&acc)[2][2][4][2], const Unit& u, int wr, int wc, int fr, int fq) const {
;     ...
;             for (int m = 0; m < 4; ++m) {
;                 const int row = row0 + ai * HALF + m * 16;
;                 float sc = 1.f; u32x4 bw0, bw1;
;                 if (has_scale) sc = xl[2560 + ai * HALF + wr * 64 + m * 16 + fr];
;                 if (MODE == 3) { bw0 = bnn[m][0]; bw1 = bnn[m][1]; }
;                 if (MODE == 0 || MODE == 1) {
; #pragma unroll
;                     for (int bj = 0; bj < 2; ++bj) {
;                         const int hf = 2 * u.pn + bj;
;                         bf16_t* dst;
;                         if (split2) dst = ((hf & 1) ? O2 : O) + (size_t)row * ldc + (hf >> 1) * 128 + wc * 32 + 8 * fq;
;                         else dst = O + (size_t)row * ldc + hf * 128 + wc * 32 + 8 * fq;
;                         f32x4 v0 = acc[ai][bj][m][0] * sc, v1 = acc[ai][bj][m][1] * sc;
;                         if (MODE == 1) {
; #pragma unroll
;                             for (int e = 0; e < 4; ++e) { float a = fmaxf(v0[e], 0.f), b = fmaxf(v1[e], 0.f); v0[e] = a * a; v1[e] = b * b; }
;                         }
;                         u32x4 w; w.x = cvt_pk_bf16(v0[0], v0[1]); w.y = cvt_pk_bf16(v0[2], v0[3]); w.z = cvt_pk_bf16(v1[0], v1[1]); w.w = cvt_pk_bf16(v1[2], v1[3]);
;                         if (MODE == 1) asm volatile("global_store_dwordx4 %0, %1, off sc1\n\ts_nop 1" :: "v"(dst), "v"(w) : "memory");
;                         else *(u32x4*)dst = w;
;                     }
; template <class Epi, class Sched, bool ALIGN_EPI = false, bool SP2 = false>
; __device__ __forceinline__ void gemm_phase(PG8_LAS unsigned char* lds, const Gemm g, const Sched& S, const Epi& E) {
;     ...
;         if constexpr (ALIGN_EPI) { if (wr == 0) PG8_BAR; }
;         if constexpr (!Epi::AFTER_DRAIN) { E(acc, cur, wr, wc, fr, fq); S.done(cur); }
;         if (!has_next) break;
; #pragma unroll
;         for (int a = 0; a < 2; ++a)
; #pragma unroll
;             for (int b = 0; b < 2; ++b)
; #pragma unroll
;                 for (int m = 0; m < 4; ++m)
; #pragma unroll
;                     for (int n = 0; n < 2; ++n) acc[a][b][m][n] = (f32x4){0.f, 0.f, 0.f, 0.f};
;         cur = nxt; cA = nA; cB = nB; ++ui;
;         if constexpr (ALIGN_EPI) { if (wr == 1) PG8_BAR; }
;     }
	v_cvt_pk_bf16_f32 v72, v76, v77
	v_cvt_pk_bf16_f32 v73, v78, v79
	global_store_dwordx4 v[80:81], v[72:75], off sc1
	s_nop 1
	v_pk_mul_f32 v[74:75], v[64:65], v[64:65]
	v_max_f32_e32 v66, 0, v66
	v_max_f32_e32 v67, 0, v67
	v_max_f32_e32 v68, 0, v68
	v_max_f32_e32 v69, 0, v69
	v_max_f32_e32 v64, 0, v70
	v_max_f32_e32 v65, 0, v71
	v_pk_mul_f32 v[76:77], v[66:67], v[66:67]
	v_pk_mul_f32 v[68:69], v[68:69], v[68:69]
	v_pk_mul_f32 v[70:71], v[64:65], v[64:65]
	v_cvt_pk_bf16_f32 v66, v74, v75
	v_cvt_pk_bf16_f32 v67, v76, v77
	v_max_f32_e32 v56, 0, v56
	v_max_f32_e32 v57, 0, v57
	v_lshl_add_u64 v[72:73], v[80:81], 0, s[26:27]
	v_cvt_pk_bf16_f32 v64, v68, v69
	v_cvt_pk_bf16_f32 v65, v70, v71
	global_store_dwordx4 v[72:73], v[64:67], off sc1
	s_nop 1
	v_pk_mul_f32 v[66:67], v[56:57], v[56:57]
	v_max_f32_e32 v58, 0, v58
	v_max_f32_e32 v59, 0, v59
	v_max_f32_e32 v60, 0, v60
	v_max_f32_e32 v61, 0, v61
	v_max_f32_e32 v56, 0, v62
	v_max_f32_e32 v57, 0, v63
	v_pk_mul_f32 v[68:69], v[58:59], v[58:59]
	s_mov_b64 s[6:7], 0x100000
	v_pk_mul_f32 v[60:61], v[60:61], v[60:61]
	v_pk_mul_f32 v[62:63], v[56:57], v[56:57]
	v_cvt_pk_bf16_f32 v58, v66, v67
	v_cvt_pk_bf16_f32 v59, v68, v69
	v_max_f32_e32 v48, 0, v48
	v_max_f32_e32 v49, 0, v49
	v_lshl_add_u64 v[64:65], v[140:141], 0, s[6:7]
	v_cvt_pk_bf16_f32 v56, v60, v61
	v_cvt_pk_bf16_f32 v57, v62, v63
	global_store_dwordx4 v[64:65], v[56:59], off sc1
	s_nop 1
	v_pk_mul_f32 v[58:59], v[48:49], v[48:49]
	v_max_f32_e32 v50, 0, v50
	v_max_f32_e32 v51, 0, v51
	v_max_f32_e32 v52, 0, v52
	v_max_f32_e32 v53, 0, v53
	v_max_f32_e32 v48, 0, v54
	v_max_f32_e32 v49, 0, v55
	v_pk_mul_f32 v[60:61], v[50:51], v[50:51]
	s_mov_b64 s[6:7], 0x100100
	v_pk_mul_f32 v[52:53], v[52:53], v[52:53]
	v_pk_mul_f32 v[54:55], v[48:49], v[48:49]
	v_cvt_pk_bf16_f32 v50, v58, v59
	v_cvt_pk_bf16_f32 v51, v60, v61
	v_max_f32_e32 v40, 0, v40
	v_max_f32_e32 v41, 0, v41
	v_lshl_add_u64 v[56:57], v[140:141], 0, s[6:7]
	v_cvt_pk_bf16_f32 v48, v52, v53
	v_cvt_pk_bf16_f32 v49, v54, v55
	global_store_dwordx4 v[56:57], v[48:51], off sc1
	s_nop 1
	v_pk_mul_f32 v[50:51], v[40:41], v[40:41]
	v_max_f32_e32 v42, 0, v42
	v_max_f32_e32 v43, 0, v43
	v_max_f32_e32 v44, 0, v44
	v_max_f32_e32 v45, 0, v45
	v_max_f32_e32 v40, 0, v46
	v_max_f32_e32 v41, 0, v47
	v_pk_mul_f32 v[52:53], v[42:43], v[42:43]
	s_mov_b64 s[6:7], 0x120000
	v_pk_mul_f32 v[44:45], v[44:45], v[44:45]
	v_pk_mul_f32 v[46:47], v[40:41], v[40:41]
	v_cvt_pk_bf16_f32 v42, v50, v51
	v_cvt_pk_bf16_f32 v43, v52, v53
	v_max_f32_e32 v32, 0, v32
	v_max_f32_e32 v33, 0, v33
	v_lshl_add_u64 v[48:49], v[140:141], 0, s[6:7]
	v_cvt_pk_bf16_f32 v40, v44, v45
	v_cvt_pk_bf16_f32 v41, v46, v47
	global_store_dwordx4 v[48:49], v[40:43], off sc1
	s_nop 1
	v_pk_mul_f32 v[42:43], v[32:33], v[32:33]
	v_max_f32_e32 v34, 0, v34
	v_max_f32_e32 v35, 0, v35
	v_max_f32_e32 v36, 0, v36
	v_max_f32_e32 v37, 0, v37
	v_max_f32_e32 v32, 0, v38
	v_max_f32_e32 v33, 0, v39
	v_pk_mul_f32 v[44:45], v[34:35], v[34:35]
	s_mov_b64 s[6:7], 0x120100
	v_pk_mul_f32 v[36:37], v[36:37], v[36:37]
	v_pk_mul_f32 v[38:39], v[32:33], v[32:33]
	v_cvt_pk_bf16_f32 v34, v42, v43
	v_cvt_pk_bf16_f32 v35, v44, v45
	v_max_f32_e32 v24, 0, v24
	v_max_f32_e32 v25, 0, v25
	v_lshl_add_u64 v[40:41], v[140:141], 0, s[6:7]
	v_cvt_pk_bf16_f32 v32, v36, v37
	v_cvt_pk_bf16_f32 v33, v38, v39
	global_store_dwordx4 v[40:41], v[32:35], off sc1
	s_nop 1
	v_pk_mul_f32 v[34:35], v[24:25], v[24:25]
	v_max_f32_e32 v26, 0, v26
	v_max_f32_e32 v27, 0, v27
	v_max_f32_e32 v28, 0, v28
	v_max_f32_e32 v29, 0, v29
	v_max_f32_e32 v24, 0, v30
	v_max_f32_e32 v25, 0, v31
	v_pk_mul_f32 v[36:37], v[26:27], v[26:27]
	s_mov_b64 s[6:7], 0x140000
	v_pk_mul_f32 v[28:29], v[28:29], v[28:29]
	v_pk_mul_f32 v[30:31], v[24:25], v[24:25]
	v_cvt_pk_bf16_f32 v26, v34, v35
	v_cvt_pk_bf16_f32 v27, v36, v37
	v_max_f32_e32 v16, 0, v16
	v_max_f32_e32 v17, 0, v17
	v_lshl_add_u64 v[32:33], v[140:141], 0, s[6:7]
	v_cvt_pk_bf16_f32 v24, v28, v29
	v_cvt_pk_bf16_f32 v25, v30, v31
	global_store_dwordx4 v[32:33], v[24:27], off sc1
	s_nop 1
	v_pk_mul_f32 v[26:27], v[16:17], v[16:17]
	v_max_f32_e32 v18, 0, v18
	v_max_f32_e32 v19, 0, v19
	v_max_f32_e32 v20, 0, v20
	v_max_f32_e32 v21, 0, v21
	v_max_f32_e32 v16, 0, v22
	v_max_f32_e32 v17, 0, v23
	v_pk_mul_f32 v[28:29], v[18:19], v[18:19]
	s_mov_b64 s[6:7], 0x140100
	v_pk_mul_f32 v[20:21], v[20:21], v[20:21]
	v_pk_mul_f32 v[22:23], v[16:17], v[16:17]
	v_cvt_pk_bf16_f32 v18, v26, v27
	v_cvt_pk_bf16_f32 v19, v28, v29
	v_max_f32_e32 v8, 0, v8
	v_max_f32_e32 v9, 0, v9
	v_lshl_add_u64 v[24:25], v[140:141], 0, s[6:7]
	v_cvt_pk_bf16_f32 v16, v20, v21
	v_cvt_pk_bf16_f32 v17, v22, v23
	global_store_dwordx4 v[24:25], v[16:19], off sc1
	s_nop 1
	v_pk_mul_f32 v[18:19], v[8:9], v[8:9]
	v_max_f32_e32 v10, 0, v10
	v_max_f32_e32 v11, 0, v11
	v_max_f32_e32 v12, 0, v12
	v_max_f32_e32 v13, 0, v13
	v_max_f32_e32 v8, 0, v14
	v_max_f32_e32 v9, 0, v15
	v_pk_mul_f32 v[20:21], v[10:11], v[10:11]
	s_mov_b64 s[6:7], 0x160000
	v_pk_mul_f32 v[12:13], v[12:13], v[12:13]
	v_pk_mul_f32 v[14:15], v[8:9], v[8:9]
	v_cvt_pk_bf16_f32 v10, v18, v19
	v_cvt_pk_bf16_f32 v11, v20, v21
	v_max_f32_e32 v0, 0, v0
	v_max_f32_e32 v1, 0, v1
	v_lshl_add_u64 v[16:17], v[140:141], 0, s[6:7]
	v_cvt_pk_bf16_f32 v8, v12, v13
	v_cvt_pk_bf16_f32 v9, v14, v15
	global_store_dwordx4 v[16:17], v[8:11], off sc1
	s_nop 1
	v_pk_mul_f32 v[10:11], v[0:1], v[0:1]
	v_max_f32_e32 v2, 0, v2
	v_max_f32_e32 v4, 0, v4
	v_max_f32_e32 v5, 0, v5
	v_max_f32_e32 v0, 0, v6
	v_max_f32_e32 v1, 0, v7
	v_max_f32_e32 v3, 0, v3
	s_mov_b64 s[6:7], 0x160100
	v_pk_mul_f32 v[4:5], v[4:5], v[4:5]
	v_pk_mul_f32 v[6:7], v[0:1], v[0:1]
	v_pk_mul_f32 v[12:13], v[2:3], v[2:3]
	v_lshl_add_u64 v[8:9], v[140:141], 0, s[6:7]
	v_cvt_pk_bf16_f32 v0, v4, v5
	v_cvt_pk_bf16_f32 v1, v6, v7
	v_cvt_pk_bf16_f32 v2, v10, v11
	v_cvt_pk_bf16_f32 v3, v12, v13
	global_store_dwordx4 v[8:9], v[0:3], off sc1
	s_nop 1
	s_andn2_b64 vcc, exec, s[38:39]
	s_mov_b64 s[6:7], -1
	s_cbranch_vccnz .LBB0_1058
	s_andn2_b64 vcc, exec, s[0:1]
	s_cbranch_vccnz .LBB0_1057
	s_barrier
	s_branch .LBB0_1057
